# combo15 with counted waits in the P1 shift-table copy (each LDS store waits only for its own load instead of all 16)
# speedup vs baseline: 1.0002x; 1.0002x over previous
; __device__ __forceinline__ void transpose_item(LAS unsigned char* lds, const TItem& it, int wv) {
;     ...
;     const bool hb = it.bias != nullptr;
;     if (hb) {
;         for (int i = tid; i < NB * D; i += 512) shl[i] = it.shift[(size_t)(i >> 11) * MODS_LD + (i & 2047)];
;         __syncthreads();
.LBB0_119:
	v_ashrrev_i32_e32 v6, 11, v0
	v_ashrrev_i32_e32 v8, 11, v1
	v_and_b32_e32 v10, 0x7ff, v0
	v_add_u32_e32 v12, 0x400, v0
	v_mul_hi_i32_i24_e32 v7, 0x12000, v6
	v_mul_i32_i24_e32 v6, 0x12000, v6
	v_and_b32_e32 v14, 0x7ff, v1
	v_add_u32_e32 v11, 0x400, v1
	v_mul_hi_i32_i24_e32 v9, 0x12000, v8
	v_mul_i32_i24_e32 v8, 0x12000, v8
	v_lshlrev_b32_e32 v144, 2, v10
	v_ashrrev_i32_e32 v10, 11, v12
	v_lshl_add_u64 v[6:7], s[4:5], 0, v[6:7]
	v_ashrrev_i32_e32 v15, 11, v11
	v_and_b32_e32 v16, 0x7ff, v11
	v_and_b32_e32 v17, 0x7ff, v12
	v_lshl_add_u64 v[8:9], s[4:5], 0, v[8:9]
	v_mul_hi_i32_i24_e32 v11, 0x12000, v10
	v_mul_i32_i24_e32 v10, 0x12000, v10
	v_lshl_add_u64 v[6:7], v[6:7], 0, v[144:145]
	v_lshlrev_b32_e32 v144, 2, v14
	v_mul_hi_i32_i24_e32 v13, 0x12000, v15
	v_mul_i32_i24_e32 v12, 0x12000, v15
	v_lshl_add_u64 v[10:11], s[4:5], 0, v[10:11]
	v_lshl_add_u64 v[8:9], v[8:9], 0, v[144:145]
	v_lshlrev_b32_e32 v144, 2, v17
	v_lshl_add_u64 v[12:13], s[4:5], 0, v[12:13]
	global_load_dword v180, v[6:7], off
	global_load_dword v181, v[8:9], off
	v_lshl_add_u64 v[6:7], v[10:11], 0, v[144:145]
	v_lshlrev_b32_e32 v144, 2, v16
	v_lshl_add_u64 v[8:9], v[12:13], 0, v[144:145]
	global_load_dword v182, v[6:7], off
	s_nop 0
	global_load_dword v183, v[8:9], off
	v_add_u32_e32 v1, 0x800, v1
	v_add_u32_e32 v0, 0x800, v0
	v_ashrrev_i32_e32 v6, 11, v0
	v_ashrrev_i32_e32 v8, 11, v1
	v_and_b32_e32 v10, 0x7ff, v0
	v_add_u32_e32 v12, 0x400, v0
	v_mul_hi_i32_i24_e32 v7, 0x12000, v6
	v_mul_i32_i24_e32 v6, 0x12000, v6
	v_and_b32_e32 v14, 0x7ff, v1
	v_add_u32_e32 v11, 0x400, v1
	v_mul_hi_i32_i24_e32 v9, 0x12000, v8
	v_mul_i32_i24_e32 v8, 0x12000, v8
	v_lshlrev_b32_e32 v144, 2, v10
	v_ashrrev_i32_e32 v10, 11, v12
	v_lshl_add_u64 v[6:7], s[4:5], 0, v[6:7]
	v_ashrrev_i32_e32 v15, 11, v11
	v_and_b32_e32 v16, 0x7ff, v11
	v_and_b32_e32 v17, 0x7ff, v12
	v_lshl_add_u64 v[8:9], s[4:5], 0, v[8:9]
	v_mul_hi_i32_i24_e32 v11, 0x12000, v10
	v_mul_i32_i24_e32 v10, 0x12000, v10
	v_lshl_add_u64 v[6:7], v[6:7], 0, v[144:145]
	v_lshlrev_b32_e32 v144, 2, v14
	v_mul_hi_i32_i24_e32 v13, 0x12000, v15
	v_mul_i32_i24_e32 v12, 0x12000, v15
	v_lshl_add_u64 v[10:11], s[4:5], 0, v[10:11]
	v_lshl_add_u64 v[8:9], v[8:9], 0, v[144:145]
	v_lshlrev_b32_e32 v144, 2, v17
	v_lshl_add_u64 v[12:13], s[4:5], 0, v[12:13]
	global_load_dword v184, v[6:7], off
	global_load_dword v185, v[8:9], off
	v_lshl_add_u64 v[6:7], v[10:11], 0, v[144:145]
	v_lshlrev_b32_e32 v144, 2, v16
	v_lshl_add_u64 v[8:9], v[12:13], 0, v[144:145]
	global_load_dword v186, v[6:7], off
	s_nop 0
	global_load_dword v187, v[8:9], off
	v_add_u32_e32 v1, 0x800, v1
	v_add_u32_e32 v0, 0x800, v0
	v_ashrrev_i32_e32 v6, 11, v0
	v_ashrrev_i32_e32 v8, 11, v1
	v_and_b32_e32 v10, 0x7ff, v0
	v_add_u32_e32 v12, 0x400, v0
	v_mul_hi_i32_i24_e32 v7, 0x12000, v6
	v_mul_i32_i24_e32 v6, 0x12000, v6
	v_and_b32_e32 v14, 0x7ff, v1
	v_add_u32_e32 v11, 0x400, v1
	v_mul_hi_i32_i24_e32 v9, 0x12000, v8
	v_mul_i32_i24_e32 v8, 0x12000, v8
	v_lshlrev_b32_e32 v144, 2, v10
	v_ashrrev_i32_e32 v10, 11, v12
	v_lshl_add_u64 v[6:7], s[4:5], 0, v[6:7]
	v_ashrrev_i32_e32 v15, 11, v11
	v_and_b32_e32 v16, 0x7ff, v11
	v_and_b32_e32 v17, 0x7ff, v12
	v_lshl_add_u64 v[8:9], s[4:5], 0, v[8:9]
	v_mul_hi_i32_i24_e32 v11, 0x12000, v10
	v_mul_i32_i24_e32 v10, 0x12000, v10
	v_lshl_add_u64 v[6:7], v[6:7], 0, v[144:145]
	v_lshlrev_b32_e32 v144, 2, v14
	v_mul_hi_i32_i24_e32 v13, 0x12000, v15
	v_mul_i32_i24_e32 v12, 0x12000, v15
	v_lshl_add_u64 v[10:11], s[4:5], 0, v[10:11]
	v_lshl_add_u64 v[8:9], v[8:9], 0, v[144:145]
	v_lshlrev_b32_e32 v144, 2, v17
	v_lshl_add_u64 v[12:13], s[4:5], 0, v[12:13]
	global_load_dword v188, v[6:7], off
	global_load_dword v189, v[8:9], off
	v_lshl_add_u64 v[6:7], v[10:11], 0, v[144:145]
	v_lshlrev_b32_e32 v144, 2, v16
	v_lshl_add_u64 v[8:9], v[12:13], 0, v[144:145]
	global_load_dword v190, v[6:7], off
	s_nop 0
	global_load_dword v191, v[8:9], off
	v_add_u32_e32 v1, 0x800, v1
	v_add_u32_e32 v0, 0x800, v0
	v_ashrrev_i32_e32 v6, 11, v0
	v_ashrrev_i32_e32 v8, 11, v1
	v_and_b32_e32 v10, 0x7ff, v0
	v_add_u32_e32 v12, 0x400, v0
	v_mul_hi_i32_i24_e32 v7, 0x12000, v6
	v_mul_i32_i24_e32 v6, 0x12000, v6
	v_and_b32_e32 v14, 0x7ff, v1
	v_add_u32_e32 v11, 0x400, v1
	v_mul_hi_i32_i24_e32 v9, 0x12000, v8
	v_mul_i32_i24_e32 v8, 0x12000, v8
	v_lshlrev_b32_e32 v144, 2, v10
	v_ashrrev_i32_e32 v10, 11, v12
	v_lshl_add_u64 v[6:7], s[4:5], 0, v[6:7]
	v_ashrrev_i32_e32 v15, 11, v11
	v_and_b32_e32 v16, 0x7ff, v11
	v_and_b32_e32 v17, 0x7ff, v12
	v_lshl_add_u64 v[8:9], s[4:5], 0, v[8:9]
	v_mul_hi_i32_i24_e32 v11, 0x12000, v10
	v_mul_i32_i24_e32 v10, 0x12000, v10
	v_lshl_add_u64 v[6:7], v[6:7], 0, v[144:145]
	v_lshlrev_b32_e32 v144, 2, v14
	v_mul_hi_i32_i24_e32 v13, 0x12000, v15
	v_mul_i32_i24_e32 v12, 0x12000, v15
	v_lshl_add_u64 v[10:11], s[4:5], 0, v[10:11]
	v_lshl_add_u64 v[8:9], v[8:9], 0, v[144:145]
	v_lshlrev_b32_e32 v144, 2, v17
	v_lshl_add_u64 v[12:13], s[4:5], 0, v[12:13]
	global_load_dword v192, v[6:7], off
	global_load_dword v193, v[8:9], off
	v_lshl_add_u64 v[6:7], v[10:11], 0, v[144:145]
	v_lshlrev_b32_e32 v144, 2, v16
	v_lshl_add_u64 v[8:9], v[12:13], 0, v[144:145]
	global_load_dword v194, v[6:7], off
	s_nop 0
	global_load_dword v195, v[8:9], off
	v_add_u32_e32 v1, 0x800, v1
	v_add_u32_e32 v0, 0x800, v0
	v_add_u32_e32 v4, -8, v4
	v_add_u32_e32 v9, 0xffffe800, v5
	s_add_i32 s37, s37, 16
	v_cmp_eq_u32_e32 vcc, 0, v4
	v_mov_b32_e32 v6, s37
	s_or_b64 s[50:51], vcc, s[50:51]
	s_waitcnt vmcnt(15)
	ds_write_b32 v9, v180
	s_waitcnt vmcnt(14)
	ds_write_b32 v9, v181 offset:2048
	s_waitcnt vmcnt(13)
	ds_write_b32 v9, v182 offset:4096
	s_waitcnt vmcnt(12)
	ds_write_b32 v9, v183 offset:6144
	s_waitcnt vmcnt(11)
	ds_write_b32 v9, v184 offset:8192
	s_waitcnt vmcnt(10)
	ds_write_b32 v9, v185 offset:10240
	s_waitcnt vmcnt(9)
	ds_write_b32 v9, v186 offset:12288
	s_waitcnt vmcnt(8)
	ds_write_b32 v9, v187 offset:14336
	s_waitcnt vmcnt(7)
	ds_write_b32 v9, v188 offset:16384
	s_waitcnt vmcnt(6)
	ds_write_b32 v9, v189 offset:18432
	s_waitcnt vmcnt(5)
	ds_write_b32 v9, v190 offset:20480
	s_waitcnt vmcnt(4)
	ds_write_b32 v9, v191 offset:22528
	s_waitcnt vmcnt(3)
	ds_write_b32 v9, v192 offset:24576
	s_waitcnt vmcnt(2)
	ds_write_b32 v9, v193 offset:26624
	s_waitcnt vmcnt(1)
	ds_write_b32 v9, v194 offset:28672
	s_waitcnt vmcnt(0)
	ds_write_b32 v9, v195 offset:30720
	v_add_u32_e32 v5, 0x8000, v5
	s_andn2_b64 exec, exec, s[50:51]
	s_cbranch_execnz .LBB0_119
	s_or_b64 exec, exec, s[50:51]
	v_lshlrev_b32_e32 v4, 9, v6
